# gate-up and pair GEMM tile loop: tile-boundary realignment barriers removed (wave halves stay one barrier apart through the epilogue)
# baseline (speedup 1.0000x reference)
; #define PG8_STAGE(bufoff, gbase, voff) do { _Pragma("unroll") for (int _i = 0; _i < 2; ++_i) { \
;         const unsigned _m0 = ldsb + (unsigned)((bufoff) + _i * 8192); const char* _gb = (const char*)(gbase); \
;         asm volatile("s_mov_b32 m0, %0\n\ts_nop 0\n\tglobal_load_lds_dwordx4 %1, %2" :: "s"(_m0), "v"((voff)[_i]), "s"(_gb) : "m0", "memory"); } } while (0)
; #define PG8_LDA(dst, b, h) do { _Pragma("unroll") for (int m = 0; m < 4; ++m) _Pragma("unroll") for (int k = 0; k < 2; ++k) dst[m][k] = *(const LAS bf16x8*)(lds + PG8_SA(b, h) + aoff + m * 2048 + k * 1024); } while (0)
; #define PG8_LDB(dst, b, h) do { _Pragma("unroll") for (int n = 0; n < 2; ++n) _Pragma("unroll") for (int k = 0; k < 2; ++k) dst[n][k] = *(const LAS bf16x8*)(lds + PG8_SB(b, h) + boff + n * 2048 + k * 1024); } while (0)
; #define PG8_MMA(ai, bj, At, Bt) do { __builtin_amdgcn_s_setprio(1); _Pragma("unroll") for (int m = 0; m < 4; ++m) _Pragma("unroll") for (int n = 0; n < 2; ++n) _Pragma("unroll") for (int k = 0; k < 2; ++k) \
;         acc[ai][bj][m][n] = __builtin_amdgcn_mfma_f32_16x16x32_bf16(Bt[n][k], At[m][k], acc[ai][bj][m][n], 0, 0, 0); __builtin_amdgcn_s_setprio(0); } while (0)
; #define PG8_WAIT_V(n) asm volatile("s_waitcnt vmcnt(" #n ")" ::: "memory")
; #define PG8_WAIT_L(n) asm volatile("s_waitcnt lgkmcnt(" #n ")" ::: "memory")
; #define PG8_BAR __builtin_amdgcn_s_barrier()
; #define PG8_SCHED __builtin_amdgcn_sched_barrier(0)
; template <class Epi, bool ALIGN_EPI>
; __device__ __forceinline__ void gemm_phase(LAS unsigned char* lds, const Gemm g, const StaticOrder& S, const Epi& E) {
;     ...
;             const char* a1 = cA + (size_t)(t + 1) * kstep;
;             const char* a2 = last ? nA : cA + (size_t)(t + 2) * kstep; const char* b2 = last ? nB : cB + (size_t)(t + 2) * kstep;
;             const char* a3 = a2 + kstep; const char* b3 = b2 + kstep;
;             PG8_LDB(B0, 0, 0); PG8_LDB(B1, 0, 1); PG8_SCHED; PG8_LDA(At, 0, 0); PG8_STAGE(PG8_SA(1, 1), a1 + hstepA, voffA);
;             PG8_WAIT_V(8); PG8_WAIT_L(0); PG8_BAR; PG8_MMA(0, 0, At, B0); PG8_MMA(0, 1, At, B1); PG8_BAR; PG8_SCHED;
;             PG8_LDA(At, 0, 1); PG8_STAGE(PG8_SB(0, 0), b2, voffB); PG8_STAGE(PG8_SB(0, 1), b2 + hstepB, voffB); PG8_STAGE(PG8_SA(0, 0), a2, voffA);
;             PG8_WAIT_V(8); PG8_WAIT_L(0); PG8_BAR; PG8_MMA(1, 0, At, B0); PG8_MMA(1, 1, At, B1); PG8_BAR; PG8_SCHED;
.LBB0_306:
	v_add_u32_e32 v134, 0x10000, v185
	v_add_u32_e32 v158, 0x14000, v185
	ds_read_b128 v[74:77], v134
	ds_read_b128 v[94:97], v134 offset:1024
	ds_read_b128 v[114:117], v134 offset:2048
	ds_read_b128 v[134:137], v134 offset:3072
	ds_read_b128 v[146:149], v158
	ds_read_b128 v[150:153], v158 offset:1024
	ds_read_b128 v[154:157], v158 offset:2048
	ds_read_b128 v[158:161], v158 offset:3072
	s_add_u32 s30, s92, 0xfffc0080
	s_addc_u32 s31, s93, -1
	s_cmp_eq_u32 s50, 12
	s_cselect_b32 s60, s5, s30
	s_cselect_b32 s61, s4, s31
	s_cselect_b32 s58, s37, s41
	s_cselect_b32 s59, s35, s49
	s_add_u32 s56, s60, 0x80
	s_addc_u32 s57, s61, 0
	ds_read_b128 v[162:165], v186
	ds_read_b128 v[166:169], v186 offset:1024
	ds_read_b128 v[170:173], v186 offset:2048
	ds_read_b128 v[174:177], v186 offset:3072
	ds_read_b128 v[188:191], v186 offset:4096
	ds_read_b128 v[202:205], v186 offset:5120
	ds_read_b128 v[206:209], v186 offset:6144
	ds_read_b128 v[210:213], v186 offset:7168
	s_mov_b32 m0, s67
	s_nop 0
	global_load_lds_dwordx4 v0, s[92:93]
	s_nop 0
	s_mov_b32 m0, s65
	s_nop 0
	global_load_lds_dwordx4 v181, s[92:93]
	s_waitcnt vmcnt(8)
	s_waitcnt lgkmcnt(0)
	s_barrier
	s_setprio 1
	s_waitcnt lgkmcnt(0)
	v_mfma_f32_16x16x32_bf16 v[142:145], v[74:77], v[162:165], v[142:145]
	v_mfma_f32_16x16x32_bf16 v[142:145], v[94:97], v[166:169], v[142:145]
	v_mfma_f32_16x16x32_bf16 v[138:141], v[114:117], v[162:165], v[138:141]
	v_mfma_f32_16x16x32_bf16 v[138:141], v[134:137], v[166:169], v[138:141]
	v_mfma_f32_16x16x32_bf16 v[130:133], v[146:149], v[162:165], v[130:133]
	v_mfma_f32_16x16x32_bf16 v[130:133], v[150:153], v[166:169], v[130:133]
	v_mfma_f32_16x16x32_bf16 v[126:129], v[154:157], v[162:165], v[126:129]
	v_mfma_f32_16x16x32_bf16 v[126:129], v[158:161], v[166:169], v[126:129]
	v_mfma_f32_16x16x32_bf16 v[106:109], v[154:157], v[170:173], v[106:109]
	v_mfma_f32_16x16x32_bf16 v[106:109], v[158:161], v[174:177], v[106:109]
	v_mfma_f32_16x16x32_bf16 v[110:113], v[146:149], v[170:173], v[110:113]
	v_mfma_f32_16x16x32_bf16 v[110:113], v[150:153], v[174:177], v[110:113]
	v_mfma_f32_16x16x32_bf16 v[118:121], v[114:117], v[170:173], v[118:121]
	v_mfma_f32_16x16x32_bf16 v[118:121], v[134:137], v[174:177], v[118:121]
	v_mfma_f32_16x16x32_bf16 v[122:125], v[74:77], v[170:173], v[122:125]
	v_mfma_f32_16x16x32_bf16 v[122:125], v[94:97], v[174:177], v[122:125]
	v_mfma_f32_16x16x32_bf16 v[102:105], v[74:77], v[188:191], v[102:105]
	v_mfma_f32_16x16x32_bf16 v[102:105], v[94:97], v[202:205], v[102:105]
	v_mfma_f32_16x16x32_bf16 v[98:101], v[114:117], v[188:191], v[98:101]
	v_mfma_f32_16x16x32_bf16 v[98:101], v[134:137], v[202:205], v[98:101]
	v_mfma_f32_16x16x32_bf16 v[90:93], v[146:149], v[188:191], v[90:93]
	v_mfma_f32_16x16x32_bf16 v[90:93], v[150:153], v[202:205], v[90:93]
	v_mfma_f32_16x16x32_bf16 v[86:89], v[154:157], v[188:191], v[86:89]
	v_mfma_f32_16x16x32_bf16 v[86:89], v[158:161], v[202:205], v[86:89]
	v_mfma_f32_16x16x32_bf16 v[66:69], v[154:157], v[206:209], v[66:69]
	v_mfma_f32_16x16x32_bf16 v[66:69], v[158:161], v[210:213], v[66:69]
	v_mfma_f32_16x16x32_bf16 v[70:73], v[146:149], v[206:209], v[70:73]
	v_mfma_f32_16x16x32_bf16 v[70:73], v[150:153], v[210:213], v[70:73]
	v_mfma_f32_16x16x32_bf16 v[78:81], v[114:117], v[206:209], v[78:81]
	v_mfma_f32_16x16x32_bf16 v[78:81], v[134:137], v[210:213], v[78:81]
	v_mfma_f32_16x16x32_bf16 v[82:85], v[74:77], v[206:209], v[82:85]
	v_mfma_f32_16x16x32_bf16 v[82:85], v[94:97], v[210:213], v[82:85]
	s_setprio 0
	s_barrier
	ds_read_b128 v[162:165], v186 offset:16384
	ds_read_b128 v[166:169], v186 offset:17408
	ds_read_b128 v[170:173], v186 offset:18432
	ds_read_b128 v[174:177], v186 offset:19456
	ds_read_b128 v[188:191], v186 offset:20480
	ds_read_b128 v[202:205], v186 offset:21504
	ds_read_b128 v[206:209], v186 offset:22528
	ds_read_b128 v[210:213], v186 offset:23552
	s_mov_b32 m0, s29
	s_nop 0
	global_load_lds_dwordx4 v180, s[58:59]
	s_add_u32 s30, s58, 0x40000
	s_mov_b32 m0, s42
	s_nop 0
	global_load_lds_dwordx4 v182, s[58:59]
	s_addc_u32 s31, s59, 0
	s_mov_b32 m0, s43
	s_nop 0
	global_load_lds_dwordx4 v180, s[30:31]
	s_nop 0
	s_mov_b32 m0, s44
	s_nop 0
	global_load_lds_dwordx4 v182, s[30:31]
	s_nop 0
	s_mov_b32 m0, s15
	s_nop 0
	global_load_lds_dwordx4 v0, s[60:61]
	s_nop 0
	s_mov_b32 m0, s45
	s_nop 0
	global_load_lds_dwordx4 v181, s[60:61]
	s_waitcnt vmcnt(8)
	s_waitcnt lgkmcnt(0)
	s_barrier
	s_setprio 1
	s_waitcnt lgkmcnt(0)
	v_mfma_f32_16x16x32_bf16 v[62:65], v[74:77], v[162:165], v[62:65]
	v_mfma_f32_16x16x32_bf16 v[62:65], v[94:97], v[166:169], v[62:65]
	v_mfma_f32_16x16x32_bf16 v[58:61], v[114:117], v[162:165], v[58:61]
	v_mfma_f32_16x16x32_bf16 v[58:61], v[134:137], v[166:169], v[58:61]
	v_mfma_f32_16x16x32_bf16 v[54:57], v[146:149], v[162:165], v[54:57]
	v_mfma_f32_16x16x32_bf16 v[54:57], v[150:153], v[166:169], v[54:57]
	v_mfma_f32_16x16x32_bf16 v[50:53], v[154:157], v[162:165], v[50:53]
	v_mfma_f32_16x16x32_bf16 v[50:53], v[158:161], v[166:169], v[50:53]
	v_mfma_f32_16x16x32_bf16 v[34:37], v[154:157], v[170:173], v[34:37]
	v_mfma_f32_16x16x32_bf16 v[34:37], v[158:161], v[174:177], v[34:37]
	v_mfma_f32_16x16x32_bf16 v[38:41], v[146:149], v[170:173], v[38:41]
	v_mfma_f32_16x16x32_bf16 v[38:41], v[150:153], v[174:177], v[38:41]
	v_mfma_f32_16x16x32_bf16 v[42:45], v[114:117], v[170:173], v[42:45]
	v_mfma_f32_16x16x32_bf16 v[42:45], v[134:137], v[174:177], v[42:45]
	v_mfma_f32_16x16x32_bf16 v[46:49], v[74:77], v[170:173], v[46:49]
	v_mfma_f32_16x16x32_bf16 v[46:49], v[94:97], v[174:177], v[46:49]
	v_mfma_f32_16x16x32_bf16 v[30:33], v[74:77], v[188:191], v[30:33]
	v_mfma_f32_16x16x32_bf16 v[30:33], v[94:97], v[202:205], v[30:33]
	v_mfma_f32_16x16x32_bf16 v[26:29], v[114:117], v[188:191], v[26:29]
	v_mfma_f32_16x16x32_bf16 v[26:29], v[134:137], v[202:205], v[26:29]
	v_mfma_f32_16x16x32_bf16 v[22:25], v[146:149], v[188:191], v[22:25]
	v_mfma_f32_16x16x32_bf16 v[22:25], v[150:153], v[202:205], v[22:25]
	v_mfma_f32_16x16x32_bf16 v[18:21], v[154:157], v[188:191], v[18:21]
	v_mfma_f32_16x16x32_bf16 v[18:21], v[158:161], v[202:205], v[18:21]
	v_mfma_f32_16x16x32_bf16 v[2:5], v[154:157], v[206:209], v[2:5]
	v_mfma_f32_16x16x32_bf16 v[2:5], v[158:161], v[210:213], v[2:5]
	v_mfma_f32_16x16x32_bf16 v[6:9], v[146:149], v[206:209], v[6:9]
	v_mfma_f32_16x16x32_bf16 v[6:9], v[150:153], v[210:213], v[6:9]
	v_mfma_f32_16x16x32_bf16 v[10:13], v[114:117], v[206:209], v[10:13]
	v_mfma_f32_16x16x32_bf16 v[10:13], v[134:137], v[210:213], v[10:13]
	v_mfma_f32_16x16x32_bf16 v[14:17], v[74:77], v[206:209], v[14:17]
	v_mfma_f32_16x16x32_bf16 v[14:17], v[94:97], v[210:213], v[14:17]
	s_setprio 0
	s_barrier
; #define PG8_STAGE(bufoff, gbase, voff) do { _Pragma("unroll") for (int _i = 0; _i < 2; ++_i) { \
;         const unsigned _m0 = ldsb + (unsigned)((bufoff) + _i * 8192); const char* _gb = (const char*)(gbase); \
;         asm volatile("s_mov_b32 m0, %0\n\ts_nop 0\n\tglobal_load_lds_dwordx4 %1, %2" :: "s"(_m0), "v"((voff)[_i]), "s"(_gb) : "m0", "memory"); } } while (0)
; #define PG8_LDA(dst, b, h) do { _Pragma("unroll") for (int m = 0; m < 4; ++m) _Pragma("unroll") for (int k = 0; k < 2; ++k) dst[m][k] = *(const LAS bf16x8*)(lds + PG8_SA(b, h) + aoff + m * 2048 + k * 1024); } while (0)
; #define PG8_LDB(dst, b, h) do { _Pragma("unroll") for (int n = 0; n < 2; ++n) _Pragma("unroll") for (int k = 0; k < 2; ++k) dst[n][k] = *(const LAS bf16x8*)(lds + PG8_SB(b, h) + boff + n * 2048 + k * 1024); } while (0)
; #define PG8_MMA(ai, bj, At, Bt) do { __builtin_amdgcn_s_setprio(1); _Pragma("unroll") for (int m = 0; m < 4; ++m) _Pragma("unroll") for (int n = 0; n < 2; ++n) _Pragma("unroll") for (int k = 0; k < 2; ++k) \
;         acc[ai][bj][m][n] = __builtin_amdgcn_mfma_f32_16x16x32_bf16(Bt[n][k], At[m][k], acc[ai][bj][m][n], 0, 0, 0); __builtin_amdgcn_s_setprio(0); } while (0)
; #define PG8_WAIT_V(n) asm volatile("s_waitcnt vmcnt(" #n ")" ::: "memory")
; #define PG8_WAIT_L(n) asm volatile("s_waitcnt lgkmcnt(" #n ")" ::: "memory")
; #define PG8_BAR __builtin_amdgcn_s_barrier()
; #define PG8_SCHED __builtin_amdgcn_sched_barrier(0)
; template <class Epi, bool ALIGN_EPI>
; __device__ __forceinline__ void gemm_phase(LAS unsigned char* lds, const Gemm g, const StaticOrder& S, const Epi& E) {
;     ...
;             PG8_LDB(B0, 1, 0); PG8_LDB(B1, 1, 1); PG8_SCHED; PG8_LDA(At, 1, 0); PG8_STAGE(PG8_SA(0, 1), a2 + hstepA, voffA);
;             PG8_WAIT_V(8); PG8_WAIT_L(0); PG8_BAR; PG8_MMA(0, 0, At, B0); PG8_MMA(0, 1, At, B1); PG8_BAR; PG8_SCHED;
;             PG8_LDA(At, 1, 1); PG8_STAGE(PG8_SB(1, 0), b3, voffB); PG8_STAGE(PG8_SB(1, 1), b3 + hstepB, voffB); PG8_STAGE(PG8_SA(1, 0), a3, voffA);
;             PG8_WAIT_V(8); PG8_WAIT_L(0); PG8_BAR; PG8_MMA(1, 0, At, B0); PG8_MMA(1, 1, At, B1); PG8_BAR; PG8_SCHED;
;         }
;         if constexpr (ALIGN_EPI) { if (wr == 0) PG8_BAR; }
	v_add_u32_e32 v134, 0x18000, v185
	v_add_u32_e32 v158, 0x1c000, v185
	ds_read_b128 v[74:77], v134
	ds_read_b128 v[94:97], v134 offset:1024
	ds_read_b128 v[114:117], v134 offset:2048
	ds_read_b128 v[134:137], v134 offset:3072
	ds_read_b128 v[146:149], v158
	ds_read_b128 v[150:153], v158 offset:1024
	ds_read_b128 v[154:157], v158 offset:2048
	ds_read_b128 v[158:161], v158 offset:3072
	ds_read_b128 v[162:165], v186 offset:32768
	ds_read_b128 v[166:169], v186 offset:33792
	ds_read_b128 v[170:173], v186 offset:34816
	ds_read_b128 v[174:177], v186 offset:35840
	ds_read_b128 v[188:191], v186 offset:36864
	ds_read_b128 v[202:205], v186 offset:37888
	ds_read_b128 v[206:209], v186 offset:38912
	ds_read_b128 v[210:213], v186 offset:39936
	s_add_u32 s30, s60, 0x40000
	s_addc_u32 s31, s61, 0
	s_mov_b32 m0, s55
	s_nop 0
	global_load_lds_dwordx4 v0, s[30:31]
	s_nop 0
	s_mov_b32 m0, s88
	s_nop 0
	global_load_lds_dwordx4 v181, s[30:31]
	s_waitcnt vmcnt(8)
	s_waitcnt lgkmcnt(0)
	s_barrier
	s_setprio 1
	s_waitcnt lgkmcnt(0)
	v_mfma_f32_16x16x32_bf16 v[142:145], v[74:77], v[162:165], v[142:145]
	v_mfma_f32_16x16x32_bf16 v[142:145], v[94:97], v[166:169], v[142:145]
	v_mfma_f32_16x16x32_bf16 v[138:141], v[114:117], v[162:165], v[138:141]
	v_mfma_f32_16x16x32_bf16 v[138:141], v[134:137], v[166:169], v[138:141]
	v_mfma_f32_16x16x32_bf16 v[130:133], v[146:149], v[162:165], v[130:133]
	v_mfma_f32_16x16x32_bf16 v[130:133], v[150:153], v[166:169], v[130:133]
	v_mfma_f32_16x16x32_bf16 v[126:129], v[154:157], v[162:165], v[126:129]
	v_mfma_f32_16x16x32_bf16 v[126:129], v[158:161], v[166:169], v[126:129]
	v_mfma_f32_16x16x32_bf16 v[106:109], v[154:157], v[170:173], v[106:109]
	v_mfma_f32_16x16x32_bf16 v[106:109], v[158:161], v[174:177], v[106:109]
	v_mfma_f32_16x16x32_bf16 v[110:113], v[146:149], v[170:173], v[110:113]
	v_mfma_f32_16x16x32_bf16 v[110:113], v[150:153], v[174:177], v[110:113]
	v_mfma_f32_16x16x32_bf16 v[118:121], v[114:117], v[170:173], v[118:121]
	v_mfma_f32_16x16x32_bf16 v[118:121], v[134:137], v[174:177], v[118:121]
	v_mfma_f32_16x16x32_bf16 v[122:125], v[74:77], v[170:173], v[122:125]
	v_mfma_f32_16x16x32_bf16 v[122:125], v[94:97], v[174:177], v[122:125]
	v_mfma_f32_16x16x32_bf16 v[102:105], v[74:77], v[188:191], v[102:105]
	v_mfma_f32_16x16x32_bf16 v[102:105], v[94:97], v[202:205], v[102:105]
	v_mfma_f32_16x16x32_bf16 v[98:101], v[114:117], v[188:191], v[98:101]
	v_mfma_f32_16x16x32_bf16 v[98:101], v[134:137], v[202:205], v[98:101]
	v_mfma_f32_16x16x32_bf16 v[90:93], v[146:149], v[188:191], v[90:93]
	v_mfma_f32_16x16x32_bf16 v[90:93], v[150:153], v[202:205], v[90:93]
	v_mfma_f32_16x16x32_bf16 v[86:89], v[154:157], v[188:191], v[86:89]
	v_mfma_f32_16x16x32_bf16 v[86:89], v[158:161], v[202:205], v[86:89]
	v_mfma_f32_16x16x32_bf16 v[66:69], v[154:157], v[206:209], v[66:69]
	v_mfma_f32_16x16x32_bf16 v[66:69], v[158:161], v[210:213], v[66:69]
	v_mfma_f32_16x16x32_bf16 v[70:73], v[146:149], v[206:209], v[70:73]
	v_mfma_f32_16x16x32_bf16 v[70:73], v[150:153], v[210:213], v[70:73]
	v_mfma_f32_16x16x32_bf16 v[78:81], v[114:117], v[206:209], v[78:81]
	v_mfma_f32_16x16x32_bf16 v[78:81], v[134:137], v[210:213], v[78:81]
	v_mfma_f32_16x16x32_bf16 v[82:85], v[74:77], v[206:209], v[82:85]
	v_mfma_f32_16x16x32_bf16 v[82:85], v[94:97], v[210:213], v[82:85]
	s_setprio 0
	s_barrier
	ds_read_b128 v[162:165], v186 offset:49152
	ds_read_b128 v[166:169], v186 offset:50176
	ds_read_b128 v[170:173], v186 offset:51200
	ds_read_b128 v[174:177], v186 offset:52224
	ds_read_b128 v[188:191], v186 offset:53248
	ds_read_b128 v[202:205], v186 offset:54272
	ds_read_b128 v[206:209], v186 offset:55296
	ds_read_b128 v[210:213], v186 offset:56320
	s_add_u32 s30, s58, 0x80
	s_addc_u32 s31, s59, 0
	s_mov_b32 m0, s94
	s_nop 0
	global_load_lds_dwordx4 v180, s[30:31]
	s_nop 0
	s_mov_b32 m0, s95
	s_nop 0
	global_load_lds_dwordx4 v182, s[30:31]
	s_add_u32 s30, s58, 0x40080
	s_addc_u32 s31, s59, 0
	s_mov_b32 m0, s17
	s_nop 0
	global_load_lds_dwordx4 v180, s[30:31]
	s_nop 0
	s_mov_b32 m0, s53
	s_nop 0
	global_load_lds_dwordx4 v182, s[30:31]
	s_nop 0
	s_mov_b32 m0, s96
	s_nop 0
	global_load_lds_dwordx4 v0, s[56:57]
	s_nop 0
	s_mov_b32 m0, s97
	s_nop 0
	global_load_lds_dwordx4 v181, s[56:57]
	s_waitcnt vmcnt(8)
	s_waitcnt lgkmcnt(0)
	s_barrier
	s_setprio 1
	s_waitcnt lgkmcnt(0)
	v_mfma_f32_16x16x32_bf16 v[62:65], v[74:77], v[162:165], v[62:65]
	v_mfma_f32_16x16x32_bf16 v[62:65], v[94:97], v[166:169], v[62:65]
	v_mfma_f32_16x16x32_bf16 v[58:61], v[114:117], v[162:165], v[58:61]
	v_mfma_f32_16x16x32_bf16 v[58:61], v[134:137], v[166:169], v[58:61]
	v_mfma_f32_16x16x32_bf16 v[54:57], v[146:149], v[162:165], v[54:57]
	v_mfma_f32_16x16x32_bf16 v[54:57], v[150:153], v[166:169], v[54:57]
	v_mfma_f32_16x16x32_bf16 v[50:53], v[154:157], v[162:165], v[50:53]
	v_mfma_f32_16x16x32_bf16 v[50:53], v[158:161], v[166:169], v[50:53]
	v_mfma_f32_16x16x32_bf16 v[34:37], v[154:157], v[170:173], v[34:37]
	v_mfma_f32_16x16x32_bf16 v[34:37], v[158:161], v[174:177], v[34:37]
	v_mfma_f32_16x16x32_bf16 v[38:41], v[146:149], v[170:173], v[38:41]
	v_mfma_f32_16x16x32_bf16 v[38:41], v[150:153], v[174:177], v[38:41]
	v_mfma_f32_16x16x32_bf16 v[42:45], v[114:117], v[170:173], v[42:45]
	v_mfma_f32_16x16x32_bf16 v[42:45], v[134:137], v[174:177], v[42:45]
	v_mfma_f32_16x16x32_bf16 v[46:49], v[74:77], v[170:173], v[46:49]
	v_mfma_f32_16x16x32_bf16 v[46:49], v[94:97], v[174:177], v[46:49]
	v_mfma_f32_16x16x32_bf16 v[30:33], v[74:77], v[188:191], v[30:33]
	v_mfma_f32_16x16x32_bf16 v[30:33], v[94:97], v[202:205], v[30:33]
	v_mfma_f32_16x16x32_bf16 v[26:29], v[114:117], v[188:191], v[26:29]
	v_mfma_f32_16x16x32_bf16 v[26:29], v[134:137], v[202:205], v[26:29]
	v_mfma_f32_16x16x32_bf16 v[22:25], v[146:149], v[188:191], v[22:25]
	v_mfma_f32_16x16x32_bf16 v[22:25], v[150:153], v[202:205], v[22:25]
	v_mfma_f32_16x16x32_bf16 v[18:21], v[154:157], v[188:191], v[18:21]
	v_mfma_f32_16x16x32_bf16 v[18:21], v[158:161], v[202:205], v[18:21]
	v_mfma_f32_16x16x32_bf16 v[2:5], v[154:157], v[206:209], v[2:5]
	v_mfma_f32_16x16x32_bf16 v[2:5], v[158:161], v[210:213], v[2:5]
	v_mfma_f32_16x16x32_bf16 v[6:9], v[146:149], v[206:209], v[6:9]
	v_mfma_f32_16x16x32_bf16 v[6:9], v[150:153], v[210:213], v[6:9]
	v_mfma_f32_16x16x32_bf16 v[10:13], v[114:117], v[206:209], v[10:13]
	v_mfma_f32_16x16x32_bf16 v[10:13], v[134:137], v[210:213], v[10:13]
	v_mfma_f32_16x16x32_bf16 v[14:17], v[74:77], v[206:209], v[14:17]
	v_mfma_f32_16x16x32_bf16 v[14:17], v[94:97], v[210:213], v[14:17]
	s_setprio 0
	s_barrier
	s_add_i32 s50, s50, 2
	s_add_u32 s41, s41, 0x100
	s_addc_u32 s49, s49, 0
	s_add_u32 s92, s92, 0x100
	s_addc_u32 s93, s93, 0
	s_cmp_gt_u32 s50, 13
	s_cbranch_scc0 .LBB0_306
	v_readlane_b32 s4, v254, 46
	v_readlane_b32 s5, v254, 47
	s_and_b64 vcc, exec, s[4:5]
	s_cbranch_vccz .LBB0_309
; __device__ __forceinline__ float silu_f(float g) { return g * __builtin_amdgcn_rcpf(1.0f + __builtin_amdgcn_exp2f(g * -1.4426950408889634f)); }
; __device__ __forceinline__ void rstd8(const float* ss, int row0, float (&rs)[2][4]) {
;     f32x4 p[2][4];
; #pragma unroll
;     for (int ai = 0; ai < 2; ++ai)
; #pragma unroll
;         for (int m = 0; m < 4; ++m) p[ai][m] = *(const f32x4*)(ss + 4 * (size_t)(row0 + ai * HALF + m * 16));
; #pragma unroll
;     for (int ai = 0; ai < 2; ++ai)
; #pragma unroll
;         for (int m = 0; m < 4; ++m) rs[ai][m] = __builtin_amdgcn_rsqf(((p[ai][m].x + p[ai][m].y) + (p[ai][m].z + p[ai][m].w)) * (1.0f / D) + EPS);
; }
;     __device__ __forceinline__ void operator()(const f32x4 (&acc)[2][2][4][2], const Unit& u, int wr, int wc, int fr, int fq) const {
;         const int row0 = u.pm * BM + wr * 64 + fr, col0 = u.pn * HALF + wc * 32 + 8 * fq;
;         float rsv[2][4]; rstd8(ss, row0, rsv);
; #pragma unroll
;         for (int ai = 0; ai < 2; ++ai)
; #pragma unroll
;             for (int m = 0; m < 4; ++m) { const int row = row0 + ai * HALF + m * 16; const float rs = rsv[ai][m];
;                 f32x4 g0 = acc[ai][0][m][0] * rs, g1 = acc[ai][0][m][1] * rs; const f32x4 t0 = acc[ai][1][m][0] * rs, t1 = acc[ai][1][m][1] * rs;
;                 if (silu) {
; #pragma unroll
;                     for (int j = 0; j < 4; ++j) { g0[j] = silu_f(g0[j]); g1[j] = silu_f(g1[j]); } }
.LBB0_309:
	s_and_b64 vcc, exec, s[6:7]
	s_cbranch_vccz .Lep_fast
	s_lshl_b32 s4, s54, 8
	s_add_i32 s4, s4, s89
	v_or_b32_e32 v172, s4, v183
	v_ashrrev_i32_e32 v173, 31, v172
	v_or_b32_e32 v170, 16, v172
	v_lshl_add_u64 v[74:75], v[172:173], 4, s[24:25]
	v_ashrrev_i32_e32 v171, 31, v170
	v_lshl_add_u64 v[76:77], v[170:171], 4, s[24:25]
	flat_load_dwordx4 v[174:177], v[74:75]
	flat_load_dwordx4 v[154:157], v[76:77]
	v_or_b32_e32 v168, 32, v172
	v_or_b32_e32 v166, 48, v172
	v_ashrrev_i32_e32 v169, 31, v168
	v_ashrrev_i32_e32 v167, 31, v166
	v_add_u32_e32 v164, 0x80, v172
	v_add_u32_e32 v162, 0x90, v172
	v_lshl_add_u64 v[74:75], v[168:169], 4, s[24:25]
	v_lshl_add_u64 v[76:77], v[166:167], 4, s[24:25]
	v_ashrrev_i32_e32 v165, 31, v164
	v_ashrrev_i32_e32 v163, 31, v162
	v_add_u32_e32 v160, 0xa0, v172
	v_add_u32_e32 v158, 0xb0, v172
	flat_load_dwordx4 v[150:153], v[74:75]
	flat_load_dwordx4 v[146:149], v[76:77]
	v_lshl_add_u64 v[74:75], v[164:165], 4, s[24:25]
	v_lshl_add_u64 v[76:77], v[162:163], 4, s[24:25]
	v_ashrrev_i32_e32 v161, 31, v160
	v_ashrrev_i32_e32 v159, 31, v158
	flat_load_dwordx4 v[134:137], v[74:75]
	flat_load_dwordx4 v[114:117], v[76:77]
	v_lshl_add_u64 v[74:75], v[160:161], 4, s[24:25]
	v_lshl_add_u64 v[76:77], v[158:159], 4, s[24:25]
	flat_load_dwordx4 v[94:97], v[74:75]
	s_nop 0
	flat_load_dwordx4 v[74:77], v[76:77]
	s_and_b64 vcc, exec, s[6:7]
	s_waitcnt vmcnt(0) lgkmcnt(0)
	v_mov_b32_e32 v178, v175
	v_mov_b32_e32 v179, v176
	v_mov_b32_e32 v175, v177
	v_pk_add_f32 v[174:175], v[178:179], v[174:175]
	s_nop 0
	v_add_f32_e32 v159, v174, v175
	v_fmamk_f32 v159, v159, 0x3a800000, v224
	v_rsq_f32_e32 v174, v159
	s_nop 0
	v_pk_mul_f32 v[176:177], v[144:145], v[174:175] op_sel_hi:[1,0]
	v_pk_mul_f32 v[178:179], v[142:143], v[174:175] op_sel_hi:[1,0]
	v_pk_mul_f32 v[142:143], v[140:141], v[174:175] op_sel_hi:[1,0]
	v_pk_mul_f32 v[144:145], v[138:139], v[174:175] op_sel_hi:[1,0]
	s_cbranch_vccnz .LBB0_311
	v_mul_f32_e32 v139, 0xbfb8aa3b, v144
	v_exp_f32_e32 v139, v139
	v_mul_f32_e32 v159, 0xbfb8aa3b, v176
	v_exp_f32_e32 v159, v159
	v_mul_f32_e32 v138, 0xbfb8aa3b, v178
	v_add_f32_e32 v139, 1.0, v139
	v_rcp_f32_e32 v140, v139
	v_mul_f32_e32 v139, 0xbfb8aa3b, v179
	v_exp_f32_e32 v138, v138
	v_exp_f32_e32 v139, v139
	v_add_f32_e32 v159, 1.0, v159
	v_rcp_f32_e32 v188, v159
	v_mul_f32_e32 v159, 0xbfb8aa3b, v142
	v_add_f32_e32 v138, 1.0, v138
	v_add_f32_e32 v139, 1.0, v139
	v_exp_f32_e32 v159, v159
	v_rcp_f32_e32 v138, v138
	v_rcp_f32_e32 v139, v139
	v_mul_f32_e32 v141, 0xbfb8aa3b, v145
	v_add_f32_e32 v159, 1.0, v159
	v_rcp_f32_e32 v190, v159
	v_mul_f32_e32 v159, 0xbfb8aa3b, v177
	v_pk_mul_f32 v[178:179], v[178:179], v[138:139]
	v_mul_f32_e32 v138, 0xbfb8aa3b, v143
	v_exp_f32_e32 v141, v141
	v_exp_f32_e32 v159, v159
	v_exp_f32_e32 v138, v138
	v_add_f32_e32 v141, 1.0, v141
	v_add_f32_e32 v159, 1.0, v159
	v_add_f32_e32 v138, 1.0, v138
	v_rcp_f32_e32 v141, v141
	v_rcp_f32_e32 v189, v159
	v_rcp_f32_e32 v191, v138
	v_pk_mul_f32 v[144:145], v[144:145], v[140:141]
	v_pk_mul_f32 v[176:177], v[176:177], v[188:189]
	v_pk_mul_f32 v[142:143], v[142:143], v[190:191]

; #define PG8_BAR __builtin_amdgcn_s_barrier()
; template <class Epi, bool ALIGN_EPI>
; __device__ __forceinline__ void gemm_phase(LAS unsigned char* lds, const Gemm g, const StaticOrder& S, const Epi& E) {
;     ...
;         if (!has_next) break;
; #pragma unroll
;         for (int a = 0; a < 2; ++a)
; #pragma unroll
;             for (int b = 0; b < 2; ++b)
; #pragma unroll
;                 for (int m = 0; m < 4; ++m)
; #pragma unroll
;                     for (int n = 0; n < 2; ++n) acc[a][b][m][n] = (f32x4){0.f, 0.f, 0.f, 0.f};
;         cur = nxt; cA = nA; cB = nB; ++ui;
;         if constexpr (ALIGN_EPI) { if (wr == 1) PG8_BAR; }
.Lep_join:
	s_cbranch_vccnz .LBB0_302
	v_readlane_b32 s4, v254, 44
	v_readlane_b32 s5, v254, 45
	s_andn2_b64 vcc, exec, s[4:5]
	s_cbranch_vccnz .LBB0_301
	s_branch .LBB0_301

; #define PG8_WAIT_V(n) asm volatile("s_waitcnt vmcnt(" #n ")" ::: "memory")
; #define PG8_BAR __builtin_amdgcn_s_barrier()
; template <class Epi, bool ALIGN_EPI>
; __device__ __forceinline__ void gemm_phase(LAS unsigned char* lds, const Gemm g, const StaticOrder& S, const Epi& E) {
;     ...
;     PG8_WAIT_V(0);
;     if constexpr (!ALIGN_EPI) { if (wr == 0) PG8_BAR; }
;     PG8_BAR;
.LBB0_329:
	s_waitcnt vmcnt(0)
	v_readlane_b32 s58, v254, 35
	v_readlane_b32 s60, v254, 33
	v_readlane_b32 s94, v254, 31
	v_readlane_b32 s30, v254, 46
	v_readlane_b32 s31, v254, 47
	s_and_b64 vcc, exec, s[30:31]
	s_cbranch_vccz .Lpair_exit_noextra
	s_barrier
.Lpair_exit_noextra:
	s_barrier
	v_readlane_b32 s59, v254, 36
	v_readlane_b32 s61, v254, 34
	s_mov_b32 s68, s80
	v_readlane_b32 s95, v254, 32
	v_readlane_b32 s53, v254, 43
	v_readlane_b32 s65, v254, 42
	v_readlane_b32 s67, v254, 41
	v_readlane_b32 s80, v254, 40
	v_readlane_b32 s85, v254, 39
	v_readlane_b32 s34, v254, 38
	v_readlane_b32 s35, v254, 37
	s_cbranch_execnz .LBB0_388
